# v19 + gm_inproj K-loop: lean LDS-DMA issue (saddr-form loads, SALU-only m0 and pointer stepping instead of per-load 64-bit VALU adds + readfirstlane)
# speedup vs baseline: 1.0083x; 1.0083x over previous
.LBB0_1497:
	s_and_b32 s1, s0, 7
	s_mulk_i32 s1, 0x318
	s_ashr_i32 s6, s0, 3
	s_add_i32 s1, s1, s6
	s_mul_hi_i32 s6, s1, 0x2aaaaaab
	s_lshr_b32 s8, s6, 31
	s_ashr_i32 s6, s6, 6
	s_add_i32 s6, s6, s8
	s_lshl_b32 s8, s6, 3
	s_sub_i32 s9, 0x84, s8
	s_min_u32 s9, s9, 8
	v_cvt_f32_ubyte0_e32 v0, s9
	v_rcp_iflag_f32_e32 v0, v0
	s_sub_i32 s11, 0, s9
	s_mulk_i32 s6, 0xfe80
	s_add_i32 s6, s6, s1
	v_mul_f32_e32 v0, 0x4f7ffffe, v0
	v_cvt_u32_f32_e32 v0, v0
	s_abs_i32 s10, s6
	s_ashr_i32 s1, s6, 31
	v_add_u32_e32 v6, 0x1000, v82
	v_readfirstlane_b32 s12, v0
	s_mul_i32 s11, s11, s12
	s_mul_hi_u32 s11, s12, s11
	s_add_i32 s12, s12, s11
	s_mul_hi_u32 s11, s10, s12
	s_mul_i32 s12, s11, s9
	s_sub_i32 s10, s10, s12
	s_add_i32 s12, s11, 1
	s_sub_i32 s13, s10, s9
	s_cmp_ge_u32 s10, s9
	s_cselect_b32 s11, s12, s11
	s_cselect_b32 s10, s13, s10
	s_add_i32 s12, s11, 1
	s_cmp_ge_u32 s10, s9
	s_cselect_b32 s10, s12, s11
	s_xor_b32 s10, s10, s1
	s_sub_i32 s1, s10, s1
	s_mul_i32 s9, s1, s9
	s_sub_i32 s6, s6, s9
	s_add_i32 s8, s8, s6
	s_lshl_b32 s20, s8, 7
	s_ashr_i32 s21, s20, 31
	s_lshl_b64 s[8:9], s[20:21], 11
	v_readfirstlane_b32 s6, v82
	v_lshl_add_u64 v[0:1], v[72:73], 0, s[8:9]
	s_mov_b32 m0, s6
	s_mov_b64 s[12:13], 0x10000
	v_readfirstlane_b32 s6, v6
	v_add_u32_e32 v6, 0x2000, v82
	global_load_lds_dwordx4 v[0:1], off
	v_lshl_add_u64 v[4:5], v[0:1], 0, s[12:13]
	s_mov_b32 m0, s6
	v_readfirstlane_b32 s6, v6
	global_load_lds_dwordx4 v[4:5], off
	v_lshl_add_u64 v[4:5], v[0:1], 0, s[28:29]
	s_mov_b32 m0, s6
	s_mov_b64 s[36:37], 0x30000
	global_load_lds_dwordx4 v[4:5], off
	v_add_u32_e32 v4, 0x3000, v82
	s_lshl_b32 s24, s1, 7
	v_readfirstlane_b32 s6, v4
	v_lshl_add_u64 v[0:1], v[0:1], 0, s[36:37]
	s_mov_b32 m0, s6
	s_ashr_i32 s25, s24, 31
	global_load_lds_dwordx4 v[0:1], off
	v_add_u32_e32 v0, 0x8000, v82
	s_lshl_b64 s[10:11], s[24:25], 11
	v_readfirstlane_b32 s6, v0
	v_add_u32_e32 v4, 0x9000, v82
	v_lshl_add_u64 v[2:3], v[74:75], 0, s[10:11]
	s_mov_b32 m0, s6
	v_readfirstlane_b32 s6, v4
	v_add_u32_e32 v4, 0xa000, v82
	global_load_lds_dwordx4 v[2:3], off
	v_lshl_add_u64 v[0:1], v[2:3], 0, s[12:13]
	s_mov_b32 m0, s6
	v_readfirstlane_b32 s6, v4
	global_load_lds_dwordx4 v[0:1], off
	v_lshl_add_u64 v[0:1], v[2:3], 0, s[28:29]
	s_mov_b32 m0, s6
	v_lshl_add_u64 v[78:79], v[76:77], 0, s[8:9]
	global_load_lds_dwordx4 v[0:1], off
	v_lshl_add_u64 v[0:1], v[2:3], 0, s[36:37]
	v_add_u32_e32 v2, 0xb000, v82
	v_lshl_add_u64 v[80:81], v[76:77], 0, s[10:11]
	v_readfirstlane_b32 s6, v2
	s_mov_b32 m0, s6
	s_mov_b32 s6, 0
	global_load_lds_dwordx4 v[0:1], off
	s_waitcnt vmcnt(0)
	v_mov_b32_e32 v0, 0
	s_mov_b64 s[36:37], 0
	v_mov_b32_e32 v1, v0
	v_mov_b32_e32 v2, v0
	v_mov_b32_e32 v3, v0
	v_mov_b32_e32 v4, v0
	v_mov_b32_e32 v5, v0
	v_mov_b32_e32 v6, v0
	v_mov_b32_e32 v7, v0
	v_mov_b32_e32 v8, v0
	v_mov_b32_e32 v9, v0
	v_mov_b32_e32 v10, v0
	v_mov_b32_e32 v11, v0
	v_mov_b32_e32 v12, v0
	v_mov_b32_e32 v13, v0
	v_mov_b32_e32 v14, v0
	v_mov_b32_e32 v15, v0
	v_mov_b32_e32 v16, v0
	v_mov_b32_e32 v17, v0
	v_mov_b32_e32 v18, v0
	v_mov_b32_e32 v19, v0
	v_mov_b32_e32 v20, v0
	v_mov_b32_e32 v21, v0
	v_mov_b32_e32 v22, v0
	v_mov_b32_e32 v23, v0
	v_mov_b32_e32 v24, v0
	v_mov_b32_e32 v25, v0
	v_mov_b32_e32 v26, v0
	v_mov_b32_e32 v27, v0
	v_mov_b32_e32 v28, v0
	v_mov_b32_e32 v29, v0
	v_mov_b32_e32 v30, v0
	v_mov_b32_e32 v31, v0
	v_mov_b32_e32 v32, v0
	v_mov_b32_e32 v33, v0
	v_mov_b32_e32 v34, v0
	v_mov_b32_e32 v35, v0
	v_mov_b32_e32 v36, v0
	v_mov_b32_e32 v37, v0
	v_mov_b32_e32 v38, v0
	v_mov_b32_e32 v39, v0
	v_mov_b32_e32 v40, v0
	v_mov_b32_e32 v41, v0
	v_mov_b32_e32 v42, v0
	v_mov_b32_e32 v43, v0
	v_mov_b32_e32 v44, v0
	v_mov_b32_e32 v45, v0
	v_mov_b32_e32 v46, v0
	v_mov_b32_e32 v47, v0
	v_mov_b32_e32 v48, v0
	v_mov_b32_e32 v49, v0
	v_mov_b32_e32 v50, v0
	v_mov_b32_e32 v51, v0
	v_mov_b32_e32 v52, v0
	v_mov_b32_e32 v53, v0
	v_mov_b32_e32 v54, v0
	v_mov_b32_e32 v55, v0
	v_mov_b32_e32 v56, v0
	v_mov_b32_e32 v57, v0
	v_mov_b32_e32 v58, v0
	v_mov_b32_e32 v59, v0
	v_mov_b32_e32 v60, v0
	v_mov_b32_e32 v61, v0
	v_mov_b32_e32 v62, v0
	v_mov_b32_e32 v63, v0
	v_readlane_b32 s100, v182, 21
	v_readlane_b32 s101, v182, 22
	v_readlane_b32 s12, v183, 53
	v_readlane_b32 s13, v183, 54
	v_lshrrev_b32_e32 v160, 3, v104
	v_lshrrev_b32_e32 v161, 4, v104
	v_lshlrev_b32_e32 v160, 11, v160
	v_xor_b32_e32 v161, v161, v104
	s_add_u32 s100, s100, s8
	s_addc_u32 s101, s101, s9
	s_add_u32 s100, s100, 0x80
	s_addc_u32 s101, s101, 0
	s_add_u32 s12, s12, s10
	s_addc_u32 s13, s13, s11
	s_add_u32 s12, s12, 0x80
	s_addc_u32 s13, s13, 0
	v_and_b32_e32 v161, 7, v161
	v_readfirstlane_b32 s11, v82
	v_lshl_or_b32 v160, v161, 4, v160
	v_add_u32_e32 v161, 0x10000, v160
	v_add_u32_e32 v162, 0x20000, v160
	v_add_u32_e32 v163, 0x30000, v160
	s_waitcnt vmcnt(0) lgkmcnt(0)
	s_barrier
.LBB0_1498:
	s_and_b32 s10, s6, 0x2000
	s_xor_b32 s8, s10, 0x2000
	s_lshl_b32 s8, s8, 1
	s_add_u32 s8, s8, s11
	s_add_u32 m0, s8, 0
	s_add_u32 s9, s8, 0x1000
	global_load_lds_dwordx4 v160, s[100:101]
	s_mov_b32 m0, s9
	s_add_u32 s9, s8, 0x2000
	global_load_lds_dwordx4 v161, s[100:101]
	s_mov_b32 m0, s9
	s_add_u32 s9, s8, 0x3000
	global_load_lds_dwordx4 v162, s[100:101]
	s_mov_b32 m0, s9
	s_add_u32 s9, s8, 0x8000
	global_load_lds_dwordx4 v163, s[100:101]
	s_mov_b32 m0, s9
	s_add_u32 s9, s8, 0x9000
	global_load_lds_dwordx4 v160, s[12:13]
	s_mov_b32 m0, s9
	s_add_u32 s9, s8, 0xa000
	global_load_lds_dwordx4 v161, s[12:13]
	s_mov_b32 m0, s9
	s_add_u32 s9, s8, 0xb000
	global_load_lds_dwordx4 v162, s[12:13]
	s_mov_b32 m0, s9
	s_add_u32 s100, s100, 0x80
	global_load_lds_dwordx4 v163, s[12:13]
	s_addc_u32 s101, s101, 0
	s_add_u32 s12, s12, 0x80
	s_addc_u32 s13, s13, 0
	s_lshl_b32 s8, s10, 1
	v_add_u32_e32 v68, s8, v84
	v_add_u32_e32 v140, s8, v83
	v_add_u32_e32 v120, v68, v90
	v_add_u32_e32 v136, v140, v90
	ds_read_b128 v[92:95], v120
	ds_read_b128 v[96:99], v120 offset:2048
	ds_read_b128 v[100:103], v120 offset:4096
	ds_read_b128 v[120:123], v120 offset:6144
	ds_read_b128 v[124:127], v136 offset:32768
	ds_read_b128 v[128:131], v136 offset:34816
	ds_read_b128 v[132:135], v136 offset:36864
	ds_read_b128 v[136:139], v136 offset:38912
	s_setprio 1
	s_waitcnt lgkmcnt(0)
	v_mfma_f32_16x16x32_bf16 v[60:63], v[124:127], v[92:95], v[60:63]
	v_mfma_f32_16x16x32_bf16 v[56:59], v[128:131], v[92:95], v[56:59]
	v_mfma_f32_16x16x32_bf16 v[52:55], v[132:135], v[92:95], v[52:55]
	v_mfma_f32_16x16x32_bf16 v[48:51], v[136:139], v[92:95], v[48:51]
	v_mfma_f32_16x16x32_bf16 v[44:47], v[124:127], v[96:99], v[44:47]
	v_mfma_f32_16x16x32_bf16 v[40:43], v[128:131], v[96:99], v[40:43]
	v_mfma_f32_16x16x32_bf16 v[36:39], v[132:135], v[96:99], v[36:39]
	v_mfma_f32_16x16x32_bf16 v[32:35], v[136:139], v[96:99], v[32:35]
	v_mfma_f32_16x16x32_bf16 v[28:31], v[124:127], v[100:103], v[28:31]
	v_mfma_f32_16x16x32_bf16 v[24:27], v[128:131], v[100:103], v[24:27]
	v_mfma_f32_16x16x32_bf16 v[20:23], v[132:135], v[100:103], v[20:23]
	v_mfma_f32_16x16x32_bf16 v[16:19], v[136:139], v[100:103], v[16:19]
	v_mfma_f32_16x16x32_bf16 v[12:15], v[124:127], v[120:123], v[12:15]
	v_mfma_f32_16x16x32_bf16 v[8:11], v[128:131], v[120:123], v[8:11]
	v_mfma_f32_16x16x32_bf16 v[4:7], v[132:135], v[120:123], v[4:7]
	v_mfma_f32_16x16x32_bf16 v[0:3], v[136:139], v[120:123], v[0:3]
	s_setprio 0
	v_add_u32_e32 v68, v68, v91
	ds_read_b128 v[92:95], v68
	ds_read_b128 v[96:99], v68 offset:2048
	ds_read_b128 v[100:103], v68 offset:4096
	ds_read_b128 v[120:123], v68 offset:6144
	v_add_u32_e32 v68, v140, v91
	ds_read_b128 v[124:127], v68 offset:32768
	ds_read_b128 v[128:131], v68 offset:34816
	ds_read_b128 v[132:135], v68 offset:36864
	ds_read_b128 v[136:139], v68 offset:38912
	s_setprio 1
	s_waitcnt lgkmcnt(0)
	v_mfma_f32_16x16x32_bf16 v[60:63], v[124:127], v[92:95], v[60:63]
	v_mfma_f32_16x16x32_bf16 v[56:59], v[128:131], v[92:95], v[56:59]
	v_mfma_f32_16x16x32_bf16 v[52:55], v[132:135], v[92:95], v[52:55]
	v_mfma_f32_16x16x32_bf16 v[48:51], v[136:139], v[92:95], v[48:51]
	v_mfma_f32_16x16x32_bf16 v[44:47], v[124:127], v[96:99], v[44:47]
	v_mfma_f32_16x16x32_bf16 v[40:43], v[128:131], v[96:99], v[40:43]
	v_mfma_f32_16x16x32_bf16 v[36:39], v[132:135], v[96:99], v[36:39]
	v_mfma_f32_16x16x32_bf16 v[32:35], v[136:139], v[96:99], v[32:35]
	v_mfma_f32_16x16x32_bf16 v[28:31], v[124:127], v[100:103], v[28:31]
	v_mfma_f32_16x16x32_bf16 v[24:27], v[128:131], v[100:103], v[24:27]
	v_mfma_f32_16x16x32_bf16 v[20:23], v[132:135], v[100:103], v[20:23]
	v_mfma_f32_16x16x32_bf16 v[16:19], v[136:139], v[100:103], v[16:19]
	v_mfma_f32_16x16x32_bf16 v[12:15], v[124:127], v[120:123], v[12:15]
	v_mfma_f32_16x16x32_bf16 v[8:11], v[128:131], v[120:123], v[8:11]
	v_mfma_f32_16x16x32_bf16 v[4:7], v[132:135], v[120:123], v[4:7]
	v_mfma_f32_16x16x32_bf16 v[0:3], v[136:139], v[120:123], v[0:3]
	s_setprio 0
	s_addk_i32 s6, 0x2000
	s_waitcnt vmcnt(0)
	s_add_u32 s36, s36, 0x80
	s_addc_u32 s37, s37, 0
	s_cmpk_lg_i32 s36, 0x780
	s_waitcnt vmcnt(0)
	s_barrier
	s_cbranch_scc1 .LBB0_1498
	ds_read_b128 v[78:81], v85 offset:55296
	ds_read_b128 v[92:95], v85 offset:53248
	ds_read_b128 v[96:99], v85 offset:51200
	ds_read_b128 v[100:103], v85 offset:49152
	ds_read_b128 v[120:123], v86 offset:22528
	ds_read_b128 v[124:127], v86 offset:20480
	ds_read_b128 v[128:131], v86 offset:18432
	ds_read_b128 v[132:135], v86 offset:16384
	s_setprio 1
	s_waitcnt lgkmcnt(0)
	v_mfma_f32_16x16x32_bf16 v[60:63], v[100:103], v[132:135], v[60:63]
	v_mfma_f32_16x16x32_bf16 v[56:59], v[96:99], v[132:135], v[56:59]
	v_mfma_f32_16x16x32_bf16 v[52:55], v[92:95], v[132:135], v[52:55]
	v_mfma_f32_16x16x32_bf16 v[48:51], v[78:81], v[132:135], v[48:51]
	v_mfma_f32_16x16x32_bf16 v[44:47], v[100:103], v[128:131], v[44:47]
	v_mfma_f32_16x16x32_bf16 v[40:43], v[96:99], v[128:131], v[40:43]
	v_mfma_f32_16x16x32_bf16 v[36:39], v[92:95], v[128:131], v[36:39]
	v_mfma_f32_16x16x32_bf16 v[32:35], v[78:81], v[128:131], v[32:35]
	v_mfma_f32_16x16x32_bf16 v[28:31], v[100:103], v[124:127], v[28:31]
	v_mfma_f32_16x16x32_bf16 v[24:27], v[96:99], v[124:127], v[24:27]
	v_mfma_f32_16x16x32_bf16 v[20:23], v[92:95], v[124:127], v[20:23]
	v_mfma_f32_16x16x32_bf16 v[16:19], v[78:81], v[124:127], v[16:19]
	v_mfma_f32_16x16x32_bf16 v[12:15], v[100:103], v[120:123], v[12:15]
	v_mfma_f32_16x16x32_bf16 v[8:11], v[96:99], v[120:123], v[8:11]
	v_mfma_f32_16x16x32_bf16 v[4:7], v[92:95], v[120:123], v[4:7]
	v_mfma_f32_16x16x32_bf16 v[0:3], v[78:81], v[120:123], v[0:3]
	s_setprio 0
	ds_read_b128 v[78:81], v87 offset:16384
	ds_read_b128 v[92:95], v87 offset:18432
	ds_read_b128 v[96:99], v87 offset:20480
	ds_read_b128 v[100:103], v87 offset:22528
	ds_read_b128 v[120:123], v88 offset:49152
	ds_read_b128 v[124:127], v88 offset:51200
	ds_read_b128 v[128:131], v88 offset:53248
	ds_read_b128 v[132:135], v88 offset:55296
	s_setprio 1
	s_waitcnt lgkmcnt(3)
	v_mfma_f32_16x16x32_bf16 v[60:63], v[120:123], v[78:81], v[60:63]
	s_waitcnt lgkmcnt(2)
	v_mfma_f32_16x16x32_bf16 v[56:59], v[124:127], v[78:81], v[56:59]
	s_waitcnt lgkmcnt(1)
	v_mfma_f32_16x16x32_bf16 v[52:55], v[128:131], v[78:81], v[52:55]
	s_waitcnt lgkmcnt(0)
	v_mfma_f32_16x16x32_bf16 v[48:51], v[132:135], v[78:81], v[48:51]
	v_mfma_f32_16x16x32_bf16 v[44:47], v[120:123], v[92:95], v[44:47]
	v_mfma_f32_16x16x32_bf16 v[40:43], v[124:127], v[92:95], v[40:43]
	v_mfma_f32_16x16x32_bf16 v[36:39], v[128:131], v[92:95], v[36:39]
	v_mfma_f32_16x16x32_bf16 v[32:35], v[132:135], v[92:95], v[32:35]
	v_mfma_f32_16x16x32_bf16 v[28:31], v[120:123], v[96:99], v[28:31]
	v_mfma_f32_16x16x32_bf16 v[24:27], v[124:127], v[96:99], v[24:27]
	v_mfma_f32_16x16x32_bf16 v[20:23], v[128:131], v[96:99], v[20:23]
	v_mfma_f32_16x16x32_bf16 v[16:19], v[132:135], v[96:99], v[16:19]
	v_mfma_f32_16x16x32_bf16 v[12:15], v[120:123], v[100:103], v[12:15]
	v_mfma_f32_16x16x32_bf16 v[8:11], v[124:127], v[100:103], v[8:11]
	v_mfma_f32_16x16x32_bf16 v[4:7], v[128:131], v[100:103], v[4:7]
	v_mfma_f32_16x16x32_bf16 v[0:3], v[132:135], v[100:103], v[0:3]
	s_setprio 0
	s_ashr_i32 s1, s1, 4
	s_mul_hi_i32 s6, s1, 0x4200000
	s_mul_i32 s1, s1, 0x4200000
	s_add_u32 s8, s90, s1
	v_add_u32_e32 v78, s20, v71
	s_addc_u32 s9, s91, s6
	s_and_b32 s1, s24, 0x780
	v_ashrrev_i32_e32 v79, 31, v78
	v_or_b32_e32 v68, s1, v89
	v_lshlrev_b64 v[80:81], 12, v[78:79]
	v_lshl_add_u64 v[80:81], s[8:9], 0, v[80:81]
	v_lshlrev_b32_e32 v68, 1, v68
	v_cvt_pk_bf16_f32 v60, v60, v61
	v_cvt_pk_bf16_f32 v61, v62, v63
	v_lshl_add_u64 v[62:63], v[80:81], 0, v[68:69]
	v_cvt_pk_bf16_f32 v48, v48, v49
	v_cvt_pk_bf16_f32 v49, v50, v51
	s_waitcnt vmcnt(0)
	s_barrier
	global_store_dwordx2 v[62:63], v[48:49], off offset:96
	v_or_b32_e32 v48, 16, v78
	v_ashrrev_i32_e32 v49, 31, v48
	v_lshlrev_b64 v[48:49], 12, v[48:49]
	v_lshl_add_u64 v[48:49], s[8:9], 0, v[48:49]
	v_cvt_pk_bf16_f32 v44, v44, v45
	v_cvt_pk_bf16_f32 v45, v46, v47
	v_lshl_add_u64 v[46:47], v[48:49], 0, v[68:69]
	v_cvt_pk_bf16_f32 v32, v32, v33
	v_cvt_pk_bf16_f32 v33, v34, v35
	global_store_dwordx2 v[46:47], v[32:33], off offset:96
	v_or_b32_e32 v32, 32, v78
	v_ashrrev_i32_e32 v33, 31, v32
	v_lshlrev_b64 v[32:33], 12, v[32:33]
	v_lshl_add_u64 v[32:33], s[8:9], 0, v[32:33]
	v_cvt_pk_bf16_f32 v28, v28, v29
	v_cvt_pk_bf16_f32 v29, v30, v31
	v_lshl_add_u64 v[30:31], v[32:33], 0, v[68:69]
	v_cvt_pk_bf16_f32 v16, v16, v17
	v_cvt_pk_bf16_f32 v17, v18, v19
	global_store_dwordx2 v[30:31], v[16:17], off offset:96
	v_or_b32_e32 v16, 48, v78
	v_ashrrev_i32_e32 v17, 31, v16
	v_lshlrev_b64 v[16:17], 12, v[16:17]
	v_lshl_add_u64 v[16:17], s[8:9], 0, v[16:17]
	s_add_i32 s0, s0, s84
	v_cvt_pk_bf16_f32 v56, v56, v57
	v_cvt_pk_bf16_f32 v57, v58, v59
	v_cvt_pk_bf16_f32 v52, v52, v53
	v_cvt_pk_bf16_f32 v53, v54, v55
	v_cvt_pk_bf16_f32 v40, v40, v41
	v_cvt_pk_bf16_f32 v41, v42, v43
	v_cvt_pk_bf16_f32 v36, v36, v37
	v_cvt_pk_bf16_f32 v37, v38, v39
	v_cvt_pk_bf16_f32 v24, v24, v25
	v_cvt_pk_bf16_f32 v25, v26, v27
	v_cvt_pk_bf16_f32 v20, v20, v21
	v_cvt_pk_bf16_f32 v21, v22, v23
	v_cvt_pk_bf16_f32 v12, v12, v13
	v_cvt_pk_bf16_f32 v13, v14, v15
	v_lshl_add_u64 v[14:15], v[16:17], 0, v[68:69]
	v_cvt_pk_bf16_f32 v8, v8, v9
	v_cvt_pk_bf16_f32 v9, v10, v11
	v_cvt_pk_bf16_f32 v4, v4, v5
	v_cvt_pk_bf16_f32 v5, v6, v7
	v_cvt_pk_bf16_f32 v0, v0, v1
	v_cvt_pk_bf16_f32 v1, v2, v3
	s_cmpk_lt_i32 s0, 0x18c0
	global_store_dwordx2 v[62:63], v[60:61], off
	global_store_dwordx2 v[62:63], v[56:57], off offset:32
	global_store_dwordx2 v[62:63], v[52:53], off offset:64
	global_store_dwordx2 v[46:47], v[44:45], off
	global_store_dwordx2 v[46:47], v[40:41], off offset:32
	global_store_dwordx2 v[46:47], v[36:37], off offset:64
	global_store_dwordx2 v[30:31], v[28:29], off
	global_store_dwordx2 v[30:31], v[24:25], off offset:32
	global_store_dwordx2 v[30:31], v[20:21], off offset:64
	global_store_dwordx2 v[14:15], v[12:13], off
	global_store_dwordx2 v[14:15], v[8:9], off offset:32
	global_store_dwordx2 v[14:15], v[4:5], off offset:64
	global_store_dwordx2 v[14:15], v[0:1], off offset:96
	s_cbranch_scc1 .LBB0_1497
